# plus staging LDS writes issued early in the PV half-step (before the O MFMAs) instead of at its tail
# speedup vs baseline: 1.0330x; 1.0061x over previous
; #define LAS __attribute__((address_space(3)))
; #define MFMA32(a, b, c) __builtin_amdgcn_mfma_f32_32x32x16_bf16((a), (b), (c), 0, 0, 0)
; #define AT_ISSUE_V(jn) do { const int jc_ = (jn) < ntm1 ? (jn) : ntm1; const size_t vo_ = (size_t)jc_ * 16384; vs0 = *(const u32x4*)(bV0 + vo_ + voff); vs1 = *(const u32x4*)(bV1 + vo_ + voff); } while (0)
; __device__ __forceinline__ void at_pv_half(const LAS unsigned char* vp, const bf16x8 (&pf)[4], f32x16 (&O)[4], f32x16& L) {
;     bf16x8 va[8], vb[8];
; #pragma unroll
;     for (int e = 0; e < 2; ++e)
; #pragma unroll
;         for (int ks = 0; ks < 4; ++ks) va[e * 4 + ks] = *(const LAS bf16x8*)(vp + e * 32 * AT_ROWB + 32 * ks);
; #pragma unroll
;     for (int e = 0; e < 2; ++e)
; #pragma unroll
;         for (int ks = 0; ks < 4; ++ks) vb[e * 4 + ks] = *(const LAS bf16x8*)(vp + (2 + e) * 32 * AT_ROWB + 32 * ks);
;     const short one = (short)0x3F80; const bf16x8 ones = {one, one, one, one, one, one, one, one};
;     __builtin_amdgcn_sched_barrier(0);
;     __builtin_amdgcn_s_setprio(1);
; #pragma unroll
;     for (int ks = 0; ks < 4; ++ks) L = MFMA32(ones, pf[ks], L);
;     __builtin_amdgcn_sched_barrier(0);
; #pragma unroll
;     for (int ks = 0; ks < 4; ++ks) { O[0] = MFMA32(va[ks], pf[ks], O[0]); O[1] = MFMA32(va[4 + ks], pf[ks], O[1]); }
; #pragma unroll
;     for (int ks = 0; ks < 4; ++ks) { O[2] = MFMA32(vb[ks], pf[ks], O[2]); O[3] = MFMA32(vb[4 + ks], pf[ks], O[3]); }
;     __builtin_amdgcn_s_setprio(0);
; }
; __device__ __forceinline__ void attn_item(LAS unsigned char* lds, const bf16_t* Q, const bf16_t* Kb, const bf16_t* VT, bf16_t* aout, const float* subg, float lam, float omli, float kbound, int head, int qb) {
;     ...
;             const LAS unsigned char* stg = lds + (j & 1) * AT_KST; const LAS unsigned char* pst = lds + ((j + 1) & 1) * AT_KST; const int kbase = j * 64;
;             AT_ISSUE_V(j + 1);
;             if (j > 0 && kbase - 64 <= qmax) at_pv_half(pst + vfo, pf, O, L);
;             AT_WRITE_K(j + 1);
;             __syncthreads();
;             __builtin_amdgcn_s_setprio(3);
;             { const int jc_ = (j + 2) < ntm1 ? (j + 2) : ntm1; const size_t ko_ = (size_t)jc_ * 8192; const char* pga = bK1 + ko_ + koff; const char* pgb = bK2 + ko_ + koff;
;               at_qk_half(online, kbase <= qmax, stg + kfo, ks0, ks1, pga, pgb, qf, q, q0, kbase, hh, mrun, O, L, pf); }
.LBB0_295:
	s_add_i32 s44, s45, 1
	s_bitcmp1_b32 s44, 0
	s_cselect_b32 s53, 0x4800, 0
	s_min_i32 s58, s44, s41
	s_lshl_b64 s[54:55], s[58:59], 14
	v_lshl_add_u64 v[96:97], v[208:209], 0, s[54:55]
	v_lshl_add_u64 v[98:99], v[210:211], 0, s[54:55]
	global_load_dwordx4 v[146:149], v[96:97], off
	global_load_dwordx4 v[150:153], v[98:99], off
	s_add_i32 s56, s53, 0
	s_cmp_eq_u32 s45, 0
	s_cselect_b64 s[54:55], -1, 0
	s_add_i32 s53, s1, 0xffffff81
	s_cmp_gt_i32 s53, s40
	s_cselect_b64 s[60:61], -1, 0
	s_or_b64 s[54:55], s[54:55], s[60:61]
	s_and_b64 vcc, exec, s[54:55]
	s_cbranch_vccnz .LBB0_297
	v_add_u32_e32 v184, s56, v228
	ds_read_b128 v[96:99], v184 offset:36864
	ds_read_b128 v[154:157], v184 offset:41472
	ds_read_b128 v[170:173], v184 offset:46080
	ds_read_b128 v[236:239], v184 offset:50688
	ds_read_b128 v[100:103], v184 offset:36896
	ds_read_b128 v[158:161], v184 offset:41504
	ds_read_b128 v[174:177], v184 offset:46112
	ds_read_b128 v[240:243], v184 offset:50720
	ds_read_b128 v[104:107], v184 offset:36928
	ds_read_b128 v[162:165], v184 offset:41536
	ds_read_b128 v[178:181], v184 offset:46144
	ds_read_b128 v[244:247], v184 offset:50752
	ds_read_b128 v[108:111], v184 offset:36960
	ds_read_b128 v[166:169], v184 offset:41568
	ds_read_b128 v[232:235], v184 offset:46176
	ds_read_b128 v[248:251], v184 offset:50784
	s_setprio 1
	v_mfma_f32_16x16x32_bf16 v[64:67], v[76:79], v[80:83], v[64:67]
	v_mfma_f32_16x16x32_bf16 v[64:67], v[76:79], v[88:91], v[64:67]
	v_mfma_f32_16x16x32_bf16 v[64:67], v[76:79], v[84:87], v[64:67]
	v_mfma_f32_16x16x32_bf16 v[64:67], v[76:79], v[92:95], v[64:67]
	v_add_u32_e32 v185, s56, v212
	s_waitcnt vmcnt(3)
	ds_write_b128 v185, v[142:145]
	s_waitcnt vmcnt(2)
	ds_write_b128 v185, v[138:141] offset:9216
	s_waitcnt lgkmcnt(15)
	v_mfma_f32_32x32x16_bf16 v[48:63], v[96:99], v[80:83], v[48:63]
	s_waitcnt lgkmcnt(15)
	v_mfma_f32_32x32x16_bf16 v[32:47], v[154:157], v[80:83], v[32:47]
	s_waitcnt lgkmcnt(15)
	v_mfma_f32_32x32x16_bf16 v[16:31], v[170:173], v[80:83], v[16:31]
	s_waitcnt lgkmcnt(14)
	v_mfma_f32_32x32x16_bf16 v[0:15], v[236:239], v[80:83], v[0:15]
	s_waitcnt lgkmcnt(13)
	v_mfma_f32_32x32x16_bf16 v[48:63], v[100:103], v[88:91], v[48:63]
	s_waitcnt lgkmcnt(12)
	v_mfma_f32_32x32x16_bf16 v[32:47], v[158:161], v[88:91], v[32:47]
	s_waitcnt lgkmcnt(11)
	v_mfma_f32_32x32x16_bf16 v[16:31], v[174:177], v[88:91], v[16:31]
	s_waitcnt lgkmcnt(10)
	v_mfma_f32_32x32x16_bf16 v[0:15], v[240:243], v[88:91], v[0:15]
	s_waitcnt lgkmcnt(9)
	v_mfma_f32_32x32x16_bf16 v[48:63], v[104:107], v[84:87], v[48:63]
	s_waitcnt lgkmcnt(8)
	v_mfma_f32_32x32x16_bf16 v[32:47], v[162:165], v[84:87], v[32:47]
	s_waitcnt lgkmcnt(7)
	v_mfma_f32_32x32x16_bf16 v[16:31], v[178:181], v[84:87], v[16:31]
	s_waitcnt lgkmcnt(6)
	v_mfma_f32_32x32x16_bf16 v[0:15], v[244:247], v[84:87], v[0:15]
	s_waitcnt lgkmcnt(5)
	v_mfma_f32_32x32x16_bf16 v[48:63], v[108:111], v[92:95], v[48:63]
	s_waitcnt lgkmcnt(4)
	v_mfma_f32_32x32x16_bf16 v[32:47], v[166:169], v[92:95], v[32:47]
	s_waitcnt lgkmcnt(3)
	v_mfma_f32_32x32x16_bf16 v[16:31], v[232:235], v[92:95], v[16:31]
	s_waitcnt lgkmcnt(2)
	v_mfma_f32_32x32x16_bf16 v[0:15], v[248:251], v[92:95], v[0:15]
	s_setprio 0
	s_branch .Lmy_wj1
.LBB0_297:
	v_add_u32_e32 v232, s56, v212
	s_waitcnt vmcnt(3)
	ds_write_b128 v232, v[142:145]
	s_waitcnt vmcnt(2)
	ds_write_b128 v232, v[138:141] offset:9216
.Lmy_wj1:
	v_add_u32_e32 v232, s56, v212
	s_bitcmp1_b32 s45, 0
	s_cselect_b32 s53, 0x4800, 0
	s_sub_i32 s57, s1, 63
	s_waitcnt lgkmcnt(0)
	s_barrier
	s_setprio 3
	s_add_i32 s45, s45, 2
	s_min_i32 s58, s45, s41
	s_lshl_b64 s[54:55], s[58:59], 13
	v_lshl_add_u64 v[100:101], v[204:205], 0, s[54:55]
	v_lshl_add_u64 v[102:103], v[206:207], 0, s[54:55]
	s_cmp_gt_i32 s57, s40
	v_add_u32_e32 v104, s53, v230
	s_setprio 3
	ds_read_b128 v[96:99], v104
	ds_read_b128 v[166:169], v104 offset:32
	ds_read_b128 v[162:165], v104 offset:64
	ds_read_b128 v[154:157], v104 offset:96
	ds_read_b128 v[178:181], v104 offset:4608
	ds_read_b128 v[170:173], v104 offset:4640
	ds_read_b128 v[174:177], v104 offset:4672
	ds_read_b128 v[158:161], v104 offset:4704
	global_load_dwordx4 v[142:145], v[100:101], off
	global_load_dwordx4 v[138:141], v[102:103], off
	s_cbranch_scc1 .LBB0_304
	s_cmp_le_i32 s1, s33
	s_cbranch_scc0 .Lmy_slow1
	s_andn2_b64 vcc, exec, s[64:65]
	s_cbranch_vccz .Lmy_slow1
	s_waitcnt lgkmcnt(7)
	v_mfma_f32_32x32x16_bf16 v[96:111], v[96:99], v[126:129], 0
	s_waitcnt lgkmcnt(6)
	v_mfma_f32_32x32x16_bf16 v[96:111], v[166:169], v[122:125], v[96:111]
	s_waitcnt lgkmcnt(5)
	v_mfma_f32_32x32x16_bf16 v[96:111], v[162:165], v[118:121], v[96:111]
	s_waitcnt lgkmcnt(4)
	v_mfma_f32_32x32x16_bf16 v[96:111], v[154:157], v[114:117], v[96:111]
	s_waitcnt lgkmcnt(3)
	v_mfma_f32_32x32x16_bf16 v[80:95], v[178:181], v[126:129], 0
	s_waitcnt lgkmcnt(2)
	v_mfma_f32_32x32x16_bf16 v[80:95], v[170:173], v[122:125], v[80:95]
	s_nop 3
	v_exp_f32_e32 v96, v96
	v_exp_f32_e32 v97, v97
	v_exp_f32_e32 v98, v98
	v_exp_f32_e32 v99, v99
	s_waitcnt lgkmcnt(1)
	v_mfma_f32_32x32x16_bf16 v[80:95], v[174:177], v[118:121], v[80:95]
	v_exp_f32_e32 v100, v100
	v_exp_f32_e32 v101, v101
	v_exp_f32_e32 v102, v102
	v_exp_f32_e32 v103, v103
	s_waitcnt lgkmcnt(0)
	v_mfma_f32_32x32x16_bf16 v[80:95], v[158:161], v[114:117], v[80:95]
	s_setprio 0
	v_exp_f32_e32 v104, v104
	v_exp_f32_e32 v105, v105
	v_exp_f32_e32 v106, v106
	v_exp_f32_e32 v107, v107
	v_exp_f32_e32 v108, v108
	v_exp_f32_e32 v109, v109
	v_exp_f32_e32 v110, v110
	v_exp_f32_e32 v111, v111
	s_nop 3
	v_exp_f32_e32 v154, v80
	v_exp_f32_e32 v155, v81
	v_exp_f32_e32 v156, v82
	v_exp_f32_e32 v157, v83
	v_exp_f32_e32 v158, v84
	v_exp_f32_e32 v159, v85
	v_exp_f32_e32 v160, v86
	v_exp_f32_e32 v161, v87
	v_exp_f32_e32 v162, v88
	v_exp_f32_e32 v163, v89
	v_exp_f32_e32 v164, v90
	v_exp_f32_e32 v165, v91
	v_exp_f32_e32 v166, v92
	v_exp_f32_e32 v167, v93
	v_exp_f32_e32 v168, v94
	v_exp_f32_e32 v169, v95
	v_cvt_pk_bf16_f32 v80, v96, v97
	v_cvt_pk_bf16_f32 v81, v98, v99
	v_cvt_pk_bf16_f32 v82, v100, v101
	v_cvt_pk_bf16_f32 v83, v102, v103
	v_cvt_pk_bf16_f32 v84, v154, v155
	v_cvt_pk_bf16_f32 v85, v156, v157
	v_cvt_pk_bf16_f32 v86, v158, v159
	v_cvt_pk_bf16_f32 v87, v160, v161
	v_cvt_pk_bf16_f32 v88, v104, v105
	v_cvt_pk_bf16_f32 v89, v106, v107
	v_cvt_pk_bf16_f32 v90, v108, v109
	v_cvt_pk_bf16_f32 v91, v110, v111
	v_cvt_pk_bf16_f32 v92, v162, v163
	v_cvt_pk_bf16_f32 v93, v164, v165
	v_cvt_pk_bf16_f32 v94, v166, v167
	v_cvt_pk_bf16_f32 v95, v168, v169
	s_branch .LBB0_304

; #define LAS __attribute__((address_space(3)))
; #define MFMA32(a, b, c) __builtin_amdgcn_mfma_f32_32x32x16_bf16((a), (b), (c), 0, 0, 0)
; #define AT_ISSUE_K(jn) do { const int jc_ = (jn) < ntm1 ? (jn) : ntm1; const size_t ko_ = (size_t)jc_ * 8192; ks0 = *(const u32x4*)(bK1 + ko_ + koff); ks1 = *(const u32x4*)(bK2 + ko_ + koff); } while (0)
; #define AT_WRITE_K(jn) do { LAS unsigned char* n_ = lds + ((jn) & 1) * AT_KST; *(LAS u32x4*)(n_ + dK1) = ks0; *(LAS u32x4*)(n_ + dK2) = ks1; } while (0)
; #define AT_WRITE_V(jn) do { LAS unsigned char* n_ = lds + ((jn) & 1) * AT_KST; *(LAS u32x4*)(n_ + dV0) = vs0; *(LAS u32x4*)(n_ + dV1) = vs1; } while (0)
; __device__ __forceinline__ void at_pv_half(const LAS unsigned char* vp, const bf16x8 (&pf)[4], f32x16 (&O)[4], f32x16& L) {
;     bf16x8 va[8], vb[8];
; #pragma unroll
;     for (int e = 0; e < 2; ++e)
; #pragma unroll
;         for (int ks = 0; ks < 4; ++ks) va[e * 4 + ks] = *(const LAS bf16x8*)(vp + e * 32 * AT_ROWB + 32 * ks);
; #pragma unroll
;     for (int e = 0; e < 2; ++e)
; #pragma unroll
;         for (int ks = 0; ks < 4; ++ks) vb[e * 4 + ks] = *(const LAS bf16x8*)(vp + (2 + e) * 32 * AT_ROWB + 32 * ks);
;     const short one = (short)0x3F80; const bf16x8 ones = {one, one, one, one, one, one, one, one};
;     __builtin_amdgcn_sched_barrier(0);
;     __builtin_amdgcn_s_setprio(1);
; #pragma unroll
;     for (int ks = 0; ks < 4; ++ks) L = MFMA32(ones, pf[ks], L);
;     __builtin_amdgcn_sched_barrier(0);
; #pragma unroll
;     for (int ks = 0; ks < 4; ++ks) { O[0] = MFMA32(va[ks], pf[ks], O[0]); O[1] = MFMA32(va[4 + ks], pf[ks], O[1]); }
; #pragma unroll
;     for (int ks = 0; ks < 4; ++ks) { O[2] = MFMA32(vb[ks], pf[ks], O[2]); O[3] = MFMA32(vb[4 + ks], pf[ks], O[3]); }
;     __builtin_amdgcn_s_setprio(0);
; __device__ __forceinline__ void attn_item(LAS unsigned char* lds, const bf16_t* Q, const bf16_t* Kb, const bf16_t* VT, bf16_t* aout, const float* subg, float lam, float omli, float kbound, int head, int qb) {
;     ...
;             __builtin_amdgcn_s_setprio(3);
;             AT_WRITE_K(j + 1);
;             __syncthreads();
;             __builtin_amdgcn_s_setprio(0);
;             AT_ISSUE_K(j + 2);
;             if (act) at_pv_half(stg + vfo, pf, O, L);
;             AT_WRITE_V(j + 1);
;             __syncthreads();
.LBB0_320:
	s_setprio 0
	s_setprio 3
	s_bitcmp1_b32 s56, 0
	s_cselect_b32 s55, 0x4800, 0
	s_waitcnt lgkmcnt(7)
	v_add_u32_e32 v96, s55, v213
	s_waitcnt vmcnt(3)
	ds_write_b128 v96, v[130:133]
	s_waitcnt vmcnt(2)
	ds_write_b128 v96, v[134:137] offset:9216
	s_waitcnt lgkmcnt(0)
	s_barrier
	s_setprio 0
	s_add_i32 s53, s53, 2
	s_min_i32 s58, s53, s41
	s_lshl_b64 s[60:61], s[58:59], 13
	v_lshl_add_u64 v[98:99], v[204:205], 0, s[60:61]
	v_lshl_add_u64 v[100:101], v[206:207], 0, s[60:61]
	global_load_dwordx4 v[130:133], v[98:99], off
	global_load_dwordx4 v[134:137], v[100:101], off
	s_andn2_b64 vcc, exec, s[0:1]
	s_cbranch_vccnz .LBB0_322
	v_add_u32_e32 v97, s54, v228
	ds_read_b128 v[98:101], v97 offset:36864
	ds_read_b128 v[150:153], v97 offset:41472
	ds_read_b128 v[166:169], v97 offset:46080
	ds_read_b128 v[234:237], v97 offset:50688
	ds_read_b128 v[102:105], v97 offset:36896
	ds_read_b128 v[154:157], v97 offset:41504
	ds_read_b128 v[170:173], v97 offset:46112
	ds_read_b128 v[238:241], v97 offset:50720
	ds_read_b128 v[106:109], v97 offset:36928
	ds_read_b128 v[158:161], v97 offset:41536
	ds_read_b128 v[176:179], v97 offset:46144
	ds_read_b128 v[242:245], v97 offset:50752
	ds_read_b128 v[146:149], v97 offset:36960
	ds_read_b128 v[162:165], v97 offset:41568
	ds_read_b128 v[230:233], v97 offset:46176
	ds_read_b128 v[246:249], v97 offset:50784
	s_setprio 1
	v_mfma_f32_16x16x32_bf16 v[64:67], v[76:79], v[80:83], v[64:67]
	v_mfma_f32_16x16x32_bf16 v[64:67], v[76:79], v[88:91], v[64:67]
	v_mfma_f32_16x16x32_bf16 v[64:67], v[76:79], v[84:87], v[64:67]
	v_mfma_f32_16x16x32_bf16 v[64:67], v[76:79], v[92:95], v[64:67]
	s_waitcnt vmcnt(3)
	ds_write_b128 v96, v[138:141] offset:36864
	s_waitcnt vmcnt(2)
	ds_write_b128 v96, v[142:145] offset:46080
	s_waitcnt lgkmcnt(15)
	v_mfma_f32_32x32x16_bf16 v[48:63], v[98:101], v[80:83], v[48:63]
	s_waitcnt lgkmcnt(15)
	v_mfma_f32_32x32x16_bf16 v[32:47], v[150:153], v[80:83], v[32:47]
	s_waitcnt lgkmcnt(15)
	v_mfma_f32_32x32x16_bf16 v[16:31], v[166:169], v[80:83], v[16:31]
	s_waitcnt lgkmcnt(14)
	v_mfma_f32_32x32x16_bf16 v[0:15], v[234:237], v[80:83], v[0:15]
	s_waitcnt lgkmcnt(13)
	v_mfma_f32_32x32x16_bf16 v[48:63], v[102:105], v[88:91], v[48:63]
	s_waitcnt lgkmcnt(12)
	v_mfma_f32_32x32x16_bf16 v[32:47], v[154:157], v[88:91], v[32:47]
	s_waitcnt lgkmcnt(11)
	v_mfma_f32_32x32x16_bf16 v[16:31], v[170:173], v[88:91], v[16:31]
	s_waitcnt lgkmcnt(10)
	v_mfma_f32_32x32x16_bf16 v[0:15], v[238:241], v[88:91], v[0:15]
	s_waitcnt lgkmcnt(9)
	v_mfma_f32_32x32x16_bf16 v[48:63], v[106:109], v[84:87], v[48:63]
	s_waitcnt lgkmcnt(8)
	v_mfma_f32_32x32x16_bf16 v[32:47], v[158:161], v[84:87], v[32:47]
	s_waitcnt lgkmcnt(7)
	v_mfma_f32_32x32x16_bf16 v[16:31], v[176:179], v[84:87], v[16:31]
	s_waitcnt lgkmcnt(6)
	v_mfma_f32_32x32x16_bf16 v[0:15], v[242:245], v[84:87], v[0:15]
	s_waitcnt lgkmcnt(5)
	v_mfma_f32_32x32x16_bf16 v[48:63], v[146:149], v[92:95], v[48:63]
	s_waitcnt lgkmcnt(4)
	v_mfma_f32_32x32x16_bf16 v[32:47], v[162:165], v[92:95], v[32:47]
	s_waitcnt lgkmcnt(3)
	v_mfma_f32_32x32x16_bf16 v[16:31], v[230:233], v[92:95], v[16:31]
	s_waitcnt lgkmcnt(2)
	v_mfma_f32_32x32x16_bf16 v[0:15], v[246:249], v[92:95], v[0:15]
	s_setprio 0
	s_branch .Lmy_wj3
.LBB0_322:
	s_waitcnt vmcnt(3)
	ds_write_b128 v96, v[138:141] offset:36864
	s_waitcnt vmcnt(2)
	ds_write_b128 v96, v[142:145] offset:46080
.Lmy_wj3:
	s_add_i32 s45, s45, 64
	s_cmp_eq_u32 s44, s56
	s_waitcnt lgkmcnt(0)
	s_barrier
	s_cbranch_scc1 .LBB0_325
	s_mov_b32 s53, s56
	s_branch .LBB0_313

; __device__ __forceinline__ void at_qk_half(const bool ONLINE, const bool act, const LAS unsigned char* kp, u32x4& pfa, u32x4& pfb, const char* pga, const char* pgb, const bf16x8 (&qf)[4], int q, int q0, int kbase, int hh, float& mrun, f32x16 (&O)[4], f32x16& L, bf16x8 (&pf)[4]) {
;     __builtin_amdgcn_s_setprio(3);
;     bf16x8 kf[8];
; #pragma unroll
;     for (int s = 0; s < 4; ++s) { kf[2 * s] = *(const LAS bf16x8*)(kp + 32 * s); kf[2 * s + 1] = *(const LAS bf16x8*)(kp + 32 * AT_ROWB + 32 * s); }
;     __builtin_amdgcn_sched_barrier(0);
;     pfa = *(const u32x4*)pga; pfb = *(const u32x4*)pgb;
;     __builtin_amdgcn_sched_barrier(0);
;     if (!act) { __builtin_amdgcn_s_setprio(0); return; }
;     f32x16 s0, s1;
; #pragma unroll
;     for (int i = 0; i < 16; ++i) { s0[i] = 0.f; s1[i] = 0.f; }
; #pragma unroll
;     for (int s = 0; s < 4; ++s) { s0 = MFMA32(kf[2 * s], qf[s], s0); s1 = MFMA32(kf[2 * s + 1], qf[s], s1); }
;     __builtin_amdgcn_s_setprio(0);
;     if (kbase + 63 > q0) {
;         const int kb = kbase + 4 * hh;
; #pragma unroll
;         for (int i = 0; i < 16; ++i) { const int kv = kb + (i & 3) + 8 * (i >> 2); if (kv > q) s0[i] = -INFINITY; if (kv + 32 > q) s1[i] = -INFINITY; }
;     }
;     if (ONLINE) {
; #pragma unroll
; __device__ __forceinline__ void at_pv_half(const LAS unsigned char* vp, const bf16x8 (&pf)[4], f32x16 (&O)[4], f32x16& L) {
;     bf16x8 va[8], vb[8];
; #pragma unroll
;     for (int e = 0; e < 2; ++e)
; #pragma unroll
;         for (int ks = 0; ks < 4; ++ks) va[e * 4 + ks] = *(const LAS bf16x8*)(vp + e * 32 * AT_ROWB + 32 * ks);
; #pragma unroll
;     for (int e = 0; e < 2; ++e)
; #pragma unroll
;         for (int ks = 0; ks < 4; ++ks) vb[e * 4 + ks] = *(const LAS bf16x8*)(vp + (2 + e) * 32 * AT_ROWB + 32 * ks);
;     const short one = (short)0x3F80; const bf16x8 ones = {one, one, one, one, one, one, one, one};
;     __builtin_amdgcn_sched_barrier(0);
;     __builtin_amdgcn_s_setprio(1);
; #pragma unroll
;     for (int ks = 0; ks < 4; ++ks) L = MFMA32(ones, pf[ks], L);
;     __builtin_amdgcn_sched_barrier(0);
; #pragma unroll
;     for (int ks = 0; ks < 4; ++ks) { O[0] = MFMA32(va[ks], pf[ks], O[0]); O[1] = MFMA32(va[4 + ks], pf[ks], O[1]); }
; #pragma unroll
;     for (int ks = 0; ks < 4; ++ks) { O[2] = MFMA32(vb[ks], pf[ks], O[2]); O[3] = MFMA32(vb[4 + ks], pf[ks], O[3]); }
;     __builtin_amdgcn_s_setprio(0);
.LBB0_333:
	s_add_i32 s38, s39, 1
	s_bitcmp1_b32 s38, 0
	s_cselect_b32 s42, 0x4800, 0
	s_min_i32 s58, s38, s22
	s_lshl_b64 s[40:41], s[58:59], 14
	v_lshl_add_u64 v[96:97], v[208:209], 0, s[40:41]
	v_lshl_add_u64 v[98:99], v[210:211], 0, s[40:41]
	global_load_dwordx4 v[146:149], v[96:97], off
	global_load_dwordx4 v[150:153], v[98:99], off
	s_add_i32 s40, s42, 0
	s_cmp_eq_u32 s39, 0
	s_cselect_b64 s[42:43], -1, 0
	s_add_i32 s41, s1, 0xffffff81
	s_cmp_gt_i32 s41, s21
	s_cselect_b64 s[44:45], -1, 0
	s_or_b64 s[42:43], s[42:43], s[44:45]
	s_and_b64 vcc, exec, s[42:43]
	s_cbranch_vccnz .LBB0_335
	v_add_u32_e32 v244, s40, v228
	ds_read_b128 v[96:99], v244 offset:36864
	ds_read_b128 v[154:157], v244 offset:41472
	ds_read_b128 v[170:173], v244 offset:46080
	ds_read_b128 v[232:235], v244 offset:50688
	ds_read_b128 v[100:103], v244 offset:36896
	ds_read_b128 v[158:161], v244 offset:41504
	ds_read_b128 v[174:177], v244 offset:46112
	ds_read_b128 v[236:239], v244 offset:50720
	ds_read_b128 v[104:107], v244 offset:36928
	ds_read_b128 v[162:165], v244 offset:41536
	ds_read_b128 v[178:181], v244 offset:46144
	ds_read_b128 v[240:243], v244 offset:50752
	ds_read_b128 v[108:111], v244 offset:36960
	ds_read_b128 v[166:169], v244 offset:41568
	ds_read_b128 v[184:187], v244 offset:46176
	ds_read_b128 v[244:247], v244 offset:50784
	s_setprio 1
	v_mfma_f32_16x16x32_bf16 v[64:67], v[76:79], v[80:83], v[64:67]
	v_mfma_f32_16x16x32_bf16 v[64:67], v[76:79], v[88:91], v[64:67]
	v_mfma_f32_16x16x32_bf16 v[64:67], v[76:79], v[84:87], v[64:67]
	v_mfma_f32_16x16x32_bf16 v[64:67], v[76:79], v[92:95], v[64:67]
	v_add_u32_e32 v249, s40, v212
	s_waitcnt vmcnt(3)
	ds_write_b128 v249, v[142:145]
	s_waitcnt vmcnt(2)
	ds_write_b128 v249, v[138:141] offset:9216
	s_waitcnt lgkmcnt(15)
	v_mfma_f32_32x32x16_bf16 v[48:63], v[96:99], v[80:83], v[48:63]
	s_waitcnt lgkmcnt(15)
	v_mfma_f32_32x32x16_bf16 v[32:47], v[154:157], v[80:83], v[32:47]
	s_waitcnt lgkmcnt(15)
	v_mfma_f32_32x32x16_bf16 v[16:31], v[170:173], v[80:83], v[16:31]
	s_waitcnt lgkmcnt(14)
	v_mfma_f32_32x32x16_bf16 v[0:15], v[232:235], v[80:83], v[0:15]
	s_waitcnt lgkmcnt(13)
	v_mfma_f32_32x32x16_bf16 v[48:63], v[100:103], v[88:91], v[48:63]
	s_waitcnt lgkmcnt(12)
	v_mfma_f32_32x32x16_bf16 v[32:47], v[158:161], v[88:91], v[32:47]
	s_waitcnt lgkmcnt(11)
	v_mfma_f32_32x32x16_bf16 v[16:31], v[174:177], v[88:91], v[16:31]
	s_waitcnt lgkmcnt(10)
	v_mfma_f32_32x32x16_bf16 v[0:15], v[236:239], v[88:91], v[0:15]
	s_waitcnt lgkmcnt(9)
	v_mfma_f32_32x32x16_bf16 v[48:63], v[104:107], v[84:87], v[48:63]
	s_waitcnt lgkmcnt(8)
	v_mfma_f32_32x32x16_bf16 v[32:47], v[162:165], v[84:87], v[32:47]
	s_waitcnt lgkmcnt(7)
	v_mfma_f32_32x32x16_bf16 v[16:31], v[178:181], v[84:87], v[16:31]
	s_waitcnt lgkmcnt(6)
	v_mfma_f32_32x32x16_bf16 v[0:15], v[240:243], v[84:87], v[0:15]
	s_waitcnt lgkmcnt(5)
	v_mfma_f32_32x32x16_bf16 v[48:63], v[108:111], v[92:95], v[48:63]
	s_waitcnt lgkmcnt(4)
	v_mfma_f32_32x32x16_bf16 v[32:47], v[166:169], v[92:95], v[32:47]
	s_waitcnt lgkmcnt(3)
	v_mfma_f32_32x32x16_bf16 v[16:31], v[184:187], v[92:95], v[16:31]
	s_waitcnt lgkmcnt(2)
	v_mfma_f32_32x32x16_bf16 v[0:15], v[244:247], v[92:95], v[0:15]
	s_setprio 0
	s_branch .Lmy_wj4
.LBB0_335:
	v_add_u32_e32 v232, s40, v212
	s_waitcnt vmcnt(3)
	ds_write_b128 v232, v[142:145]
	s_waitcnt vmcnt(2)
	ds_write_b128 v232, v[138:141] offset:9216
.Lmy_wj4:
	v_add_u32_e32 v232, s40, v212
	s_bitcmp1_b32 s39, 0
	s_cselect_b32 s42, 0x4800, 0
	s_sub_i32 s43, s1, 63
	s_waitcnt lgkmcnt(0)
	s_barrier
	s_setprio 3
	s_add_i32 s39, s39, 2
	s_min_i32 s58, s39, s22
	s_lshl_b64 s[40:41], s[58:59], 13
	v_lshl_add_u64 v[100:101], v[204:205], 0, s[40:41]
	v_lshl_add_u64 v[102:103], v[206:207], 0, s[40:41]
	s_cmp_gt_i32 s43, s21
	v_add_u32_e32 v104, s42, v230
	s_setprio 3
	ds_read_b128 v[96:99], v104
	ds_read_b128 v[166:169], v104 offset:32
	ds_read_b128 v[162:165], v104 offset:64
	ds_read_b128 v[154:157], v104 offset:96
	ds_read_b128 v[178:181], v104 offset:4608
	ds_read_b128 v[170:173], v104 offset:4640
	ds_read_b128 v[174:177], v104 offset:4672
	ds_read_b128 v[158:161], v104 offset:4704
	global_load_dwordx4 v[142:145], v[100:101], off
	global_load_dwordx4 v[138:141], v[102:103], off
	s_cbranch_scc1 .LBB0_342
	s_cmp_le_i32 s1, s33
	s_cbranch_scc0 .Lmy_slow3
	s_andn2_b64 vcc, exec, s[8:9]
	s_cbranch_vccz .Lmy_slow3
	s_waitcnt lgkmcnt(7)
	v_mfma_f32_32x32x16_bf16 v[96:111], v[96:99], v[126:129], 0
	s_waitcnt lgkmcnt(6)
	v_mfma_f32_32x32x16_bf16 v[96:111], v[166:169], v[122:125], v[96:111]
	s_waitcnt lgkmcnt(5)
	v_mfma_f32_32x32x16_bf16 v[96:111], v[162:165], v[118:121], v[96:111]
	s_waitcnt lgkmcnt(4)
	v_mfma_f32_32x32x16_bf16 v[96:111], v[154:157], v[114:117], v[96:111]
	s_waitcnt lgkmcnt(3)
	v_mfma_f32_32x32x16_bf16 v[80:95], v[178:181], v[126:129], 0
	s_waitcnt lgkmcnt(2)
	v_mfma_f32_32x32x16_bf16 v[80:95], v[170:173], v[122:125], v[80:95]
	s_nop 3
	v_exp_f32_e32 v96, v96
	v_exp_f32_e32 v97, v97
	v_exp_f32_e32 v98, v98
	v_exp_f32_e32 v99, v99
	s_waitcnt lgkmcnt(1)
	v_mfma_f32_32x32x16_bf16 v[80:95], v[174:177], v[118:121], v[80:95]
	v_exp_f32_e32 v100, v100
	v_exp_f32_e32 v101, v101
	v_exp_f32_e32 v102, v102
	v_exp_f32_e32 v103, v103
	s_waitcnt lgkmcnt(0)
	v_mfma_f32_32x32x16_bf16 v[80:95], v[158:161], v[114:117], v[80:95]
	s_setprio 0
	v_exp_f32_e32 v104, v104
	v_exp_f32_e32 v105, v105
	v_exp_f32_e32 v106, v106
	v_exp_f32_e32 v107, v107
	v_exp_f32_e32 v108, v108
	v_exp_f32_e32 v109, v109
	v_exp_f32_e32 v110, v110
	v_exp_f32_e32 v111, v111
	s_nop 3
	v_exp_f32_e32 v154, v80
	v_exp_f32_e32 v155, v81
	v_exp_f32_e32 v156, v82
	v_exp_f32_e32 v157, v83
	v_exp_f32_e32 v158, v84
	v_exp_f32_e32 v159, v85
	v_exp_f32_e32 v160, v86
	v_exp_f32_e32 v161, v87
	v_exp_f32_e32 v162, v88
	v_exp_f32_e32 v163, v89
	v_exp_f32_e32 v164, v90
	v_exp_f32_e32 v165, v91
	v_exp_f32_e32 v166, v92
	v_exp_f32_e32 v167, v93
	v_exp_f32_e32 v168, v94
	v_exp_f32_e32 v169, v95
	v_cvt_pk_bf16_f32 v80, v96, v97
	v_cvt_pk_bf16_f32 v81, v98, v99
	v_cvt_pk_bf16_f32 v82, v100, v101
	v_cvt_pk_bf16_f32 v83, v102, v103
	v_cvt_pk_bf16_f32 v84, v154, v155
	v_cvt_pk_bf16_f32 v85, v156, v157
	v_cvt_pk_bf16_f32 v86, v158, v159
	v_cvt_pk_bf16_f32 v87, v160, v161
	v_cvt_pk_bf16_f32 v88, v104, v105
	v_cvt_pk_bf16_f32 v89, v106, v107
	v_cvt_pk_bf16_f32 v90, v108, v109
	v_cvt_pk_bf16_f32 v91, v110, v111
	v_cvt_pk_bf16_f32 v92, v162, v163
	v_cvt_pk_bf16_f32 v93, v164, v165
	v_cvt_pk_bf16_f32 v94, v166, v167
	v_cvt_pk_bf16_f32 v95, v168, v169
	s_branch .LBB0_342

; #define LAS __attribute__((address_space(3)))
; #define MFMA32(a, b, c) __builtin_amdgcn_mfma_f32_32x32x16_bf16((a), (b), (c), 0, 0, 0)
; #define AT_ISSUE_K(jn) do { const int jc_ = (jn) < ntm1 ? (jn) : ntm1; const size_t ko_ = (size_t)jc_ * 8192; ks0 = *(const u32x4*)(bK1 + ko_ + koff); ks1 = *(const u32x4*)(bK2 + ko_ + koff); } while (0)
; #define AT_WRITE_K(jn) do { LAS unsigned char* n_ = lds + ((jn) & 1) * AT_KST; *(LAS u32x4*)(n_ + dK1) = ks0; *(LAS u32x4*)(n_ + dK2) = ks1; } while (0)
; #define AT_WRITE_V(jn) do { LAS unsigned char* n_ = lds + ((jn) & 1) * AT_KST; *(LAS u32x4*)(n_ + dV0) = vs0; *(LAS u32x4*)(n_ + dV1) = vs1; } while (0)
; __device__ __forceinline__ void at_pv_half(const LAS unsigned char* vp, const bf16x8 (&pf)[4], f32x16 (&O)[4], f32x16& L) {
;     bf16x8 va[8], vb[8];
; #pragma unroll
;     for (int e = 0; e < 2; ++e)
; #pragma unroll
;         for (int ks = 0; ks < 4; ++ks) va[e * 4 + ks] = *(const LAS bf16x8*)(vp + e * 32 * AT_ROWB + 32 * ks);
; #pragma unroll
;     for (int e = 0; e < 2; ++e)
; #pragma unroll
;         for (int ks = 0; ks < 4; ++ks) vb[e * 4 + ks] = *(const LAS bf16x8*)(vp + (2 + e) * 32 * AT_ROWB + 32 * ks);
;     const short one = (short)0x3F80; const bf16x8 ones = {one, one, one, one, one, one, one, one};
;     __builtin_amdgcn_sched_barrier(0);
;     __builtin_amdgcn_s_setprio(1);
; #pragma unroll
;     for (int ks = 0; ks < 4; ++ks) L = MFMA32(ones, pf[ks], L);
;     __builtin_amdgcn_sched_barrier(0);
; #pragma unroll
;     for (int ks = 0; ks < 4; ++ks) { O[0] = MFMA32(va[ks], pf[ks], O[0]); O[1] = MFMA32(va[4 + ks], pf[ks], O[1]); }
; #pragma unroll
;     for (int ks = 0; ks < 4; ++ks) { O[2] = MFMA32(vb[ks], pf[ks], O[2]); O[3] = MFMA32(vb[4 + ks], pf[ks], O[3]); }
;     __builtin_amdgcn_s_setprio(0);
; __device__ __forceinline__ void attn_item(LAS unsigned char* lds, const bf16_t* Q, const bf16_t* Kb, const bf16_t* VT, bf16_t* aout, const float* subg, float lam, float omli, float kbound, int head, int qb) {
;     ...
;             __builtin_amdgcn_s_setprio(3);
;             AT_WRITE_K(j + 1);
;             __syncthreads();
;             __builtin_amdgcn_s_setprio(0);
;             AT_ISSUE_K(j + 2);
;             if (act) at_pv_half(stg + vfo, pf, O, L);
;             AT_WRITE_V(j + 1);
;             __syncthreads();
.LBB0_358:
	s_setprio 0
	s_setprio 3
	s_bitcmp1_b32 s39, 0
	s_cselect_b32 s41, 0x4800, 0
	s_waitcnt lgkmcnt(7)
	v_add_u32_e32 v96, s41, v213
	s_waitcnt vmcnt(3)
	ds_write_b128 v96, v[130:133]
	s_waitcnt vmcnt(2)
	ds_write_b128 v96, v[134:137] offset:9216
	s_waitcnt lgkmcnt(0)
	s_barrier
	s_setprio 0
	s_add_i32 s38, s38, 2
	s_min_i32 s58, s38, s22
	s_lshl_b64 s[42:43], s[58:59], 13
	v_lshl_add_u64 v[98:99], v[204:205], 0, s[42:43]
	v_lshl_add_u64 v[100:101], v[206:207], 0, s[42:43]
	global_load_dwordx4 v[130:133], v[98:99], off
	global_load_dwordx4 v[134:137], v[100:101], off
	s_andn2_b64 vcc, exec, s[0:1]
	s_cbranch_vccnz .LBB0_360
	v_add_u32_e32 v97, s40, v228
	ds_read_b128 v[98:101], v97 offset:36864
	ds_read_b128 v[150:153], v97 offset:41472
	ds_read_b128 v[166:169], v97 offset:46080
	ds_read_b128 v[230:233], v97 offset:50688
	ds_read_b128 v[102:105], v97 offset:36896
	ds_read_b128 v[154:157], v97 offset:41504
	ds_read_b128 v[170:173], v97 offset:46112
	ds_read_b128 v[234:237], v97 offset:50720
	ds_read_b128 v[106:109], v97 offset:36928
	ds_read_b128 v[158:161], v97 offset:41536
	ds_read_b128 v[176:179], v97 offset:46144
	ds_read_b128 v[238:241], v97 offset:50752
	ds_read_b128 v[146:149], v97 offset:36960
	ds_read_b128 v[162:165], v97 offset:41568
	ds_read_b128 v[184:187], v97 offset:46176
	ds_read_b128 v[242:245], v97 offset:50784
	s_setprio 1
	v_mfma_f32_16x16x32_bf16 v[64:67], v[76:79], v[80:83], v[64:67]
	v_mfma_f32_16x16x32_bf16 v[64:67], v[76:79], v[88:91], v[64:67]
	v_mfma_f32_16x16x32_bf16 v[64:67], v[76:79], v[84:87], v[64:67]
	v_mfma_f32_16x16x32_bf16 v[64:67], v[76:79], v[92:95], v[64:67]
	s_waitcnt vmcnt(3)
	ds_write_b128 v96, v[138:141] offset:36864
	s_waitcnt vmcnt(2)
	ds_write_b128 v96, v[142:145] offset:46080
	s_waitcnt lgkmcnt(15)
	v_mfma_f32_32x32x16_bf16 v[48:63], v[98:101], v[80:83], v[48:63]
	s_waitcnt lgkmcnt(15)
	v_mfma_f32_32x32x16_bf16 v[32:47], v[150:153], v[80:83], v[32:47]
	s_waitcnt lgkmcnt(15)
	v_mfma_f32_32x32x16_bf16 v[16:31], v[166:169], v[80:83], v[16:31]
	s_waitcnt lgkmcnt(14)
	v_mfma_f32_32x32x16_bf16 v[0:15], v[230:233], v[80:83], v[0:15]
	s_waitcnt lgkmcnt(13)
	v_mfma_f32_32x32x16_bf16 v[48:63], v[102:105], v[88:91], v[48:63]
	s_waitcnt lgkmcnt(12)
	v_mfma_f32_32x32x16_bf16 v[32:47], v[154:157], v[88:91], v[32:47]
	s_waitcnt lgkmcnt(11)
	v_mfma_f32_32x32x16_bf16 v[16:31], v[170:173], v[88:91], v[16:31]
	s_waitcnt lgkmcnt(10)
	v_mfma_f32_32x32x16_bf16 v[0:15], v[234:237], v[88:91], v[0:15]
	s_waitcnt lgkmcnt(9)
	v_mfma_f32_32x32x16_bf16 v[48:63], v[106:109], v[84:87], v[48:63]
	s_waitcnt lgkmcnt(8)
	v_mfma_f32_32x32x16_bf16 v[32:47], v[158:161], v[84:87], v[32:47]
	s_waitcnt lgkmcnt(7)
	v_mfma_f32_32x32x16_bf16 v[16:31], v[176:179], v[84:87], v[16:31]
	s_waitcnt lgkmcnt(6)
	v_mfma_f32_32x32x16_bf16 v[0:15], v[238:241], v[84:87], v[0:15]
	s_waitcnt lgkmcnt(5)
	v_mfma_f32_32x32x16_bf16 v[48:63], v[146:149], v[92:95], v[48:63]
	s_waitcnt lgkmcnt(4)
	v_mfma_f32_32x32x16_bf16 v[32:47], v[162:165], v[92:95], v[32:47]
	s_waitcnt lgkmcnt(3)
	v_mfma_f32_32x32x16_bf16 v[16:31], v[184:187], v[92:95], v[16:31]
	s_waitcnt lgkmcnt(2)
	v_mfma_f32_32x32x16_bf16 v[0:15], v[242:245], v[92:95], v[0:15]
	s_setprio 0
	s_branch .Lmy_wj6

; #define LAS __attribute__((address_space(3)))
; #define AT_ISSUE_K(jn) do { const int jc_ = (jn) < ntm1 ? (jn) : ntm1; const size_t ko_ = (size_t)jc_ * 8192; ks0 = *(const u32x4*)(bK1 + ko_ + koff); ks1 = *(const u32x4*)(bK2 + ko_ + koff); } while (0)
; #define AT_WRITE_K(jn) do { LAS unsigned char* n_ = lds + ((jn) & 1) * AT_KST; *(LAS u32x4*)(n_ + dK1) = ks0; *(LAS u32x4*)(n_ + dK2) = ks1; } while (0)
; #define AT_WRITE_V(jn) do { LAS unsigned char* n_ = lds + ((jn) & 1) * AT_KST; *(LAS u32x4*)(n_ + dV0) = vs0; *(LAS u32x4*)(n_ + dV1) = vs1; } while (0)
; __device__ __forceinline__ void attn_item(LAS unsigned char* lds, const bf16_t* Q, const bf16_t* Kb, const bf16_t* VT, bf16_t* aout, const float* subg, float lam, float omli, float kbound, int head, int qb) {
;     ...
;         for (int j = 0; j < nt; ++j) {
;             const LAS unsigned char* stg = lds + (j & 1) * AT_KST; const int kbase = j * 64; const bool act = kbase <= qmax;
;             __builtin_amdgcn_s_setprio(3);
;             { const int jc_ = (j + 1) < ntm1 ? (j + 1) : ntm1; const size_t vo_ = (size_t)jc_ * 16384; const char* pga = bV0 + vo_ + voff; const char* pgb = bV1 + vo_ + voff;
;               at_qk_half(online, act, stg + kfo, vs0, vs1, pga, pgb, qf, q, q0, kbase, hh, mrun, O, L, pf); }
;             __builtin_amdgcn_s_setprio(3);
;             AT_WRITE_K(j + 1);
;             __syncthreads();
;             __builtin_amdgcn_s_setprio(0);
;             AT_ISSUE_K(j + 2);
;             if (act) at_pv_half(stg + vfo, pf, O, L);
;             AT_WRITE_V(j + 1);
;             __syncthreads();
;         }
.Lmy_wj6:
	s_add_i32 s20, s20, 64
	s_cmp_eq_u32 s19, s39
	s_waitcnt lgkmcnt(0)
	s_barrier
	s_cbranch_scc1 .LBB0_363
	s_mov_b32 s38, s39
	s_branch .LBB0_351
